# grid barrier: non-leader workgroups invalidate only their L1 (buffer_inv sc0) before polling; the XCD's last arriver still does the L2 writeback + sc1 invalidate
# speedup vs baseline: 1.0133x; 1.0071x over previous
.LBB0_29:
	v_readlane_b32 s0, v253, 38
	v_readlane_b32 s1, v253, 39
	v_cvt_f32_u32_e32 v0, v3
	v_sub_u32_e32 v5, 0, v3
	v_rcp_iflag_f32_e32 v0, v0
	s_nop 1
	global_atomic_add v4, v1, v209, s[0:1] sc0
	v_mul_f32_e32 v0, 0x4f7ffffe, v0
	v_cvt_u32_f32_e32 v0, v0
	v_mul_lo_u32 v5, v5, v0
	v_mul_hi_u32 v5, v0, v5
	v_add_u32_e32 v0, v0, v5
	s_waitcnt vmcnt(0)
	v_mul_hi_u32 v0, v4, v0
	v_mul_lo_u32 v5, v0, v3
	v_sub_u32_e32 v5, v4, v5
	v_add_u32_e32 v6, 1, v0
	v_cmp_ge_u32_e32 vcc, v5, v3
	v_add_u32_e32 v4, 1, v4
	s_nop 0
	v_cndmask_b32_e32 v0, v0, v6, vcc
	v_sub_u32_e32 v6, v5, v3
	v_cndmask_b32_e32 v5, v5, v6, vcc
	v_add_u32_e32 v6, 1, v0
	v_cmp_ge_u32_e32 vcc, v5, v3
	s_nop 1
	v_cndmask_b32_e32 v0, v0, v6, vcc
	v_mul_lo_u32 v5, v3, v0
	v_add_u32_e32 v3, v5, v3
	v_cmp_ne_u32_e32 vcc, v4, v3
	s_and_saveexec_b64 s[0:1], vcc
	s_xor_b64 s[0:1], exec, s[0:1]
	s_cbranch_execz .LBB0_43
	buffer_inv sc0
	v_readlane_b32 s2, v253, 40
	v_readlane_b32 s3, v253, 41
	s_waitcnt lgkmcnt(0)
	s_nop 3
	global_load_dword v2, v1, s[2:3] sc1
	s_waitcnt vmcnt(0)
	v_cmp_eq_u32_e32 vcc, v2, v0
	s_and_saveexec_b64 s[2:3], vcc
	s_cbranch_execz .LBB0_42
	s_mov_b32 s16, 1
	s_mov_b64 s[6:7], 0
	s_branch .LBB0_33
